# v60: + removed the compiler's full vmcnt(0) drains in front of the FoX and diff attention loops (the loops' own counted waits cover tile 0)
# baseline (speedup 1.0000x reference)
; #define ATT_WAITV(n) asm volatile("s_waitcnt vmcnt(" #n ")" ::: "memory")
; template <int MODE>
; __device__ __forceinline__ void attn_unit(const Params& P, LAS unsigned char* lds, const int b, const int h, const int qb) {
;     ...
;     const int pr = (r & 19) | ((r & 4) << 1) | ((r & 8) >> 1);
;     const unsigned kra = pr * 256, kswz = pr & 15;
;     const unsigned vra = 16384 + hh * 2048 + ((lane & 15) >> 2) * 64 + ((lane >> 4) & 1) * 32 + (lane & 3) * 8;
;     f32x16 O[4];
; #pragma unroll
;     for (int d = 0; d < 4; ++d)
; #pragma unroll
;         for (int i = 0; i < 16; ++i) O[d][i] = 0.f;
;     float m1 = ONLINE ? -INFINITY : 0.f, l1 = 0.f;
;     const int ktw_last = (q0w + 31) / 64;
;     ATT_WAITV(0); __builtin_amdgcn_s_barrier(); asm volatile("" ::: "memory");
; #pragma unroll
;     for (int i = 0; i < AL_PD; ++i) if (kt0 + i < nt) ATT_DMA(kt0 + i, i);
.LBB0_442:
	v_lshlrev_b32_e32 v0, 5, v2
	v_lshlrev_b32_e32 v2, 1, v5
	v_lshrrev_b32_e32 v3, 1, v5
	v_and_b32_e32 v193, 32, v0
	v_and_b32_e32 v0, 19, v5
	v_and_b32_e32 v2, 8, v2
	v_and_b32_e32 v3, 4, v3
	v_or3_b32 v0, v2, v0, v3
	v_lshlrev_b32_e32 v2, 4, v5
	v_and_b32_e32 v195, 0xc0, v2
	v_bitop3_b32 v2, v0, v4, 15 bitop3:0x6c
	v_lshlrev_b32_e32 v197, 4, v2
	v_or_b32_e32 v2, 2, v4
	v_bitop3_b32 v2, v0, v2, 15 bitop3:0x6c
	v_lshlrev_b32_e32 v198, 4, v2
	v_or_b32_e32 v2, 4, v4
	v_bitop3_b32 v2, v0, v2, 15 bitop3:0x6c
	v_lshlrev_b32_e32 v199, 4, v2
	v_or_b32_e32 v2, 6, v4
	v_bitop3_b32 v2, v0, v2, 15 bitop3:0x6c
	v_lshlrev_b32_e32 v200, 4, v2
	v_or_b32_e32 v2, 8, v4
	v_bitop3_b32 v2, v0, v2, 15 bitop3:0x6c
	v_lshlrev_b32_e32 v201, 4, v2
	v_or_b32_e32 v2, 10, v4
	s_ashr_i32 s8, s0, 31
	v_bitop3_b32 v2, v0, v2, 15 bitop3:0x6c
	s_lshr_b32 s8, s8, 26
	v_lshlrev_b32_e32 v202, 4, v2
	v_or_b32_e32 v2, 12, v4
	s_add_i32 s8, s8, s0
	v_bitop3_b32 v2, v0, v2, 15 bitop3:0x6c
	s_add_i32 s8, s8, 31
	v_lshlrev_b32_e32 v203, 4, v2
	v_or_b32_e32 v2, 14, v4
	s_ashr_i32 s22, s8, 6
	v_lshlrev_b32_e32 v194, 8, v0
	v_bitop3_b32 v0, v0, v2, 15 bitop3:0x6c
	s_lshl_b32 s8, s39, 6
	v_mov_b32_e32 v14, v1
	v_mov_b32_e32 v15, v1
	v_lshlrev_b32_e32 v192, 11, v4
	v_lshlrev_b32_e32 v204, 4, v0
	s_sub_i32 s8, s38, s8
	v_mov_b32_e32 v0, v1
	v_mov_b32_e32 v2, v1
	v_mov_b32_e32 v3, v1
	v_mov_b32_e32 v4, v1
	v_mov_b32_e32 v5, v1
	v_mov_b32_e32 v6, v1
	v_mov_b32_e32 v7, v1
	v_mov_b32_e32 v8, v1
	v_mov_b32_e32 v9, v1
	v_mov_b32_e32 v10, v1
	v_mov_b32_e32 v11, v1
	v_mov_b32_e32 v12, v1
	v_mov_b32_e32 v13, v1
	v_mov_b64_e32 v[78:79], v[14:15]
	v_mov_b64_e32 v[62:63], v[14:15]
	v_mov_b64_e32 v[46:47], v[14:15]
	v_mov_b64_e32 v[30:31], v[14:15]
	s_add_i32 s23, s1, -2
	s_add_i32 s66, s1, -1
	v_lshl_add_u32 v196, v96, 2, s59
	s_add_i32 s38, s8, 63
	s_add_i32 s39, s39, 4
	s_mov_b32 s67, 0
	v_mov_b32_e32 v205, 0xff800000
	v_mov_b32_e32 v191, 0
	v_mov_b64_e32 v[76:77], v[12:13]
	v_mov_b64_e32 v[74:75], v[10:11]
	v_mov_b64_e32 v[72:73], v[8:9]
	v_mov_b64_e32 v[70:71], v[6:7]
	v_mov_b64_e32 v[68:69], v[4:5]
	v_mov_b64_e32 v[66:67], v[2:3]
	v_mov_b64_e32 v[64:65], v[0:1]
	v_mov_b64_e32 v[60:61], v[12:13]
	v_mov_b64_e32 v[58:59], v[10:11]
	v_mov_b64_e32 v[56:57], v[8:9]
	v_mov_b64_e32 v[54:55], v[6:7]
	v_mov_b64_e32 v[52:53], v[4:5]
	v_mov_b64_e32 v[50:51], v[2:3]
	v_mov_b64_e32 v[48:49], v[0:1]
	v_mov_b64_e32 v[44:45], v[12:13]
	v_mov_b64_e32 v[42:43], v[10:11]
	v_mov_b64_e32 v[40:41], v[8:9]
	v_mov_b64_e32 v[38:39], v[6:7]
	v_mov_b64_e32 v[36:37], v[4:5]
	v_mov_b64_e32 v[34:35], v[2:3]
	v_mov_b64_e32 v[32:33], v[0:1]
	v_mov_b64_e32 v[28:29], v[12:13]
	v_mov_b64_e32 v[26:27], v[10:11]
	v_mov_b64_e32 v[24:25], v[8:9]
	v_mov_b64_e32 v[22:23], v[6:7]
	v_mov_b64_e32 v[20:21], v[4:5]
	v_mov_b64_e32 v[18:19], v[2:3]
	v_mov_b64_e32 v[16:17], v[0:1]
	s_branch .LBB0_445

; #define ATT_WAITV(n) asm volatile("s_waitcnt vmcnt(" #n ")" ::: "memory")
; template <int MODE>
; __device__ __forceinline__ void attn_unit(const Params& P, LAS unsigned char* lds, const int b, const int h, const int qb) {
;     ...
;     const int krow = 4 * w + (lane >> 4), kchunk = (lane & 15) ^ (krow & 15);
;     const bf16_t* kg = Kb_ + (size_t)krow * RS + kchunk * 8;
;     const int vst = 2 * w + (lane >> 5), vkey = (vst >> 2) * 8 + ((lane >> 2) & 7);
;     const bf16_t* vg = Vb_ + (size_t)vkey * RS + (vst & 3) * 32 + (lane & 3) * 8;
;     const float* cg_ = Cl + lane;
;     ...
;     const int pr = (r & 19) | ((r & 4) << 1) | ((r & 8) >> 1);
;     const unsigned kra = pr * 256, kswz = pr & 15;
;     const unsigned vra = 16384 + hh * 2048 + ((lane & 15) >> 2) * 64 + ((lane >> 4) & 1) * 32 + (lane & 3) * 8;
;     f32x16 O[4];
; #pragma unroll
;     for (int d = 0; d < 4; ++d)
; #pragma unroll
;         for (int i = 0; i < 16; ++i) O[d][i] = 0.f;
;     float m1 = ONLINE ? -INFINITY : 0.f, l1 = 0.f;
;     const int ktw_last = (q0w + 31) / 64;
;     ATT_WAITV(0); __builtin_amdgcn_s_barrier(); asm volatile("" ::: "memory");
; #pragma unroll
;     for (int i = 0; i < AL_PD; ++i) if (kt0 + i < nt) ATT_DMA(kt0 + i, i);
.LBB0_472:
	v_and_b32_e32 v2, 19, v6
	v_lshlrev_b32_e32 v3, 1, v6
	v_and_or_b32 v2, v3, 8, v2
	v_lshrrev_b32_e32 v3, 1, v6
	v_and_b32_e32 v3, 4, v3
	v_or_b32_e32 v4, v2, v3
	v_bitop3_b32 v2, v2, 15, v3 bitop3:0xc8
	v_lshlrev_b32_e32 v3, 4, v6
	v_and_b32_e32 v160, 0xc0, v3
	v_lshl_or_b32 v3, s1, 3, v7
	v_lshlrev_b32_e32 v159, 8, v4
	v_bitop3_b32 v4, v4, v3, 15 bitop3:0x6c
	v_lshlrev_b32_e32 v161, 4, v4
	v_bitop3_b32 v4, v3, v2, 2 bitop3:0x36
	v_lshlrev_b32_e32 v164, 4, v4
	v_bitop3_b32 v4, v3, v2, 4 bitop3:0x36
	v_bitop3_b32 v2, v3, v2, 6 bitop3:0x36
	s_add_i32 s38, s99, s38
	v_lshlrev_b32_e32 v148, 3, v7
	v_lshlrev_b32_e32 v166, 4, v2
	v_add_u32_e32 v2, s38, v8
	v_sub_u32_e32 v167, v2, v148
	v_add_u32_e32 v2, s39, v10
	v_ashrrev_i32_e32 v3, 31, v2
	v_lshlrev_b32_e32 v165, 4, v4
	v_lshlrev_b64 v[2:3], 8, v[2:3]
	v_and_b32_e32 v4, 15, v9
	s_and_b32 s70, s22, -8
	v_bfe_u32 v0, v6, 2, 3
	s_add_i32 s38, s97, s33
	v_lshl_or_b32 v2, v4, 4, v2
	s_add_i32 s40, s38, s98
	v_lshl_add_u64 v[152:153], s[52:53], 0, v[2:3]
	v_add_u32_e32 v2, s70, v0
	s_lshl_b32 s38, s58, 1
	v_ashrrev_i32_e32 v3, 31, v2
	v_and_b32_e32 v0, 3, v6
	s_and_b32 s38, s38, 0x80
	v_lshlrev_b64 v[2:3], 8, v[2:3]
	v_lshlrev_b32_e32 v0, 4, v0
	v_lshl_or_b32 v4, v7, 6, s38
	v_lshlrev_b32_e32 v5, 5, v10
	v_or3_b32 v2, v2, v0, v4
	v_mov_b32_e32 v14, v1
	v_mov_b32_e32 v15, v1
	v_lshlrev_b32_e32 v157, 11, v7
	v_and_b32_e32 v158, 32, v5
	s_add_i32 s22, s99, 0x80
	s_mov_b32 s41, s13
	v_lshl_add_u64 v[154:155], s[52:53], 0, v[2:3]
	v_mov_b32_e32 v0, v1
	v_mov_b32_e32 v2, v1
	v_mov_b32_e32 v3, v1
	v_mov_b32_e32 v4, v1
	v_mov_b32_e32 v5, v1
	v_mov_b32_e32 v6, v1
	v_mov_b32_e32 v7, v1
	v_mov_b32_e32 v8, v1
	v_mov_b32_e32 v9, v1
	v_mov_b32_e32 v10, v1
	v_mov_b32_e32 v11, v1
	v_mov_b32_e32 v12, v1
	v_mov_b32_e32 v13, v1
	v_mov_b64_e32 v[30:31], v[14:15]
	v_mov_b64_e32 v[46:47], v[14:15]
	v_mov_b64_e32 v[62:63], v[14:15]
	v_mov_b64_e32 v[78:79], v[14:15]
	v_lshlrev_b32_e32 v149, 7, v162
	s_lshr_b32 s22, s22, 6
	s_lshr_b32 s23, s59, 6
	s_add_i32 s75, s59, 0xffffff41
	s_lshl_b64 s[68:69], s[40:41], 21
	s_mov_b32 s38, 0
	v_mov_b32_e32 v163, 0
	s_mov_b32 s39, 63
	v_mov_b64_e32 v[28:29], v[12:13]
	v_mov_b64_e32 v[26:27], v[10:11]
	v_mov_b64_e32 v[24:25], v[8:9]
	v_mov_b64_e32 v[22:23], v[6:7]
	v_mov_b64_e32 v[20:21], v[4:5]
	v_mov_b64_e32 v[18:19], v[2:3]
	v_mov_b64_e32 v[16:17], v[0:1]
	v_mov_b64_e32 v[44:45], v[12:13]
	v_mov_b64_e32 v[42:43], v[10:11]
	v_mov_b64_e32 v[40:41], v[8:9]
	v_mov_b64_e32 v[38:39], v[6:7]
	v_mov_b64_e32 v[36:37], v[4:5]
	v_mov_b64_e32 v[34:35], v[2:3]
	v_mov_b64_e32 v[32:33], v[0:1]
	v_mov_b64_e32 v[60:61], v[12:13]
	v_mov_b64_e32 v[58:59], v[10:11]
	v_mov_b64_e32 v[56:57], v[8:9]
	v_mov_b64_e32 v[54:55], v[6:7]
	v_mov_b64_e32 v[52:53], v[4:5]
	v_mov_b64_e32 v[50:51], v[2:3]
	v_mov_b64_e32 v[48:49], v[0:1]
	v_mov_b64_e32 v[76:77], v[12:13]
	v_mov_b64_e32 v[74:75], v[10:11]
	v_mov_b64_e32 v[72:73], v[8:9]
	v_mov_b64_e32 v[70:71], v[6:7]
	v_mov_b64_e32 v[68:69], v[4:5]
	v_mov_b64_e32 v[66:67], v[2:3]
	v_mov_b64_e32 v[64:65], v[0:1]
	s_mov_b32 s40, 0
	s_branch .LBB0_475
